# v44 + RG-LRU tile loop: the 24 next-tile gather loads spread evenly through the gate-math VALU stream (first address group hoisted to right after the MFMAs) instead of two bursts
# speedup vs baseline: 1.0073x; 1.0009x over previous
; #define LAS __attribute__((address_space(3)))
; __device__ __forceinline__ void lru_fused(const bf16* XC, const bf16* Wrg_t, const bf16* PROJ, bf16* YL, const float* b_a, const float* b_x, const float* sp8,
;                                           LAS unsigned char* lds, int tid, int lane, int wave, int vcu, int G) {
;     ...
;             {
;                 bf16x8 bq[2][4];
; #pragma unroll
;                 for (int cb = 0; cb < 4; ++cb) bq[0][cb] = *(const LAS bf16x8*)(bl + cb * 16 * RG_PITCH);
; #pragma unroll
;                 for (int kb = 0; kb < 8; ++kb) {
;                     if (kb + 1 < 8) {
; #pragma unroll
;                         for (int cb = 0; cb < 4; ++cb) bq[(kb + 1) & 1][cb] = *(const LAS bf16x8*)(bl + cb * 16 * RG_PITCH + (kb + 1) * 64); }
;                     __builtin_amdgcn_sched_barrier(0);
; #pragma unroll
;                     for (int cb = 0; cb < 4; ++cb)
; #pragma unroll
;                         for (int r2 = 0; r2 < 2; ++r2) acc[r2][cb] = __builtin_amdgcn_mfma_f32_16x16x32_bf16(bq[kb & 1][cb], af[r2][kb], acc[r2][cb], 0, 0, 0);
;                     __builtin_amdgcn_sched_barrier(0);
;                 }
;             }
.LBB0_456:
	ds_read_b128 v[86:89], v170
	ds_read_b128 v[90:93], v170 offset:64
	ds_read_b128 v[94:97], v170 offset:8704
	ds_read_b128 v[98:101], v170 offset:8768
	ds_read_b128 v[106:109], v170 offset:17408
	ds_read_b128 v[154:157], v170 offset:17472
	ds_read_b128 v[160:163], v170 offset:26112
	ds_read_b128 v[174:177], v170 offset:26176
	s_waitcnt vmcnt(15)
	v_mov_b64_e32 v[198:199], v[142:143]
	s_waitcnt vmcnt(12)
	v_mov_b64_e32 v[104:105], v[144:145]
	s_waitcnt vmcnt(3)
	v_mov_b64_e32 v[102:103], v[148:149]
	s_waitcnt vmcnt(1)
	v_mov_b64_e32 v[4:5], v[150:151]
	s_waitcnt lgkmcnt(7)
	v_mfma_f32_16x16x32_bf16 v[142:145], v[86:89], v[70:73], 0
	v_mfma_f32_16x16x32_bf16 v[86:89], v[86:89], v[82:85], 0
	s_waitcnt lgkmcnt(5)
	v_mfma_f32_16x16x32_bf16 v[148:151], v[94:97], v[70:73], 0
	v_mfma_f32_16x16x32_bf16 v[94:97], v[94:97], v[82:85], 0
	s_waitcnt lgkmcnt(3)
	v_mfma_f32_16x16x32_bf16 v[182:185], v[106:109], v[70:73], 0
	v_mfma_f32_16x16x32_bf16 v[106:109], v[106:109], v[82:85], 0
	s_waitcnt lgkmcnt(1)
	v_mfma_f32_16x16x32_bf16 v[70:73], v[160:163], v[70:73], 0
	v_mfma_f32_16x16x32_bf16 v[82:85], v[160:163], v[82:85], 0
	ds_read_b128 v[160:163], v170 offset:128
	ds_read_b128 v[186:189], v170 offset:8832
	ds_read_b128 v[190:193], v170 offset:17536
	ds_read_b128 v[194:197], v170 offset:26240
	v_mfma_f32_16x16x32_bf16 v[142:145], v[90:93], v[62:65], v[142:145]
	v_mfma_f32_16x16x32_bf16 v[86:89], v[90:93], v[78:81], v[86:89]
	v_mfma_f32_16x16x32_bf16 v[90:93], v[98:101], v[62:65], v[148:151]
	v_mfma_f32_16x16x32_bf16 v[94:97], v[98:101], v[78:81], v[94:97]
	v_mfma_f32_16x16x32_bf16 v[98:101], v[154:157], v[62:65], v[182:185]
	s_waitcnt lgkmcnt(4)
	v_mfma_f32_16x16x32_bf16 v[62:65], v[174:177], v[62:65], v[70:73]
	v_mfma_f32_16x16x32_bf16 v[70:73], v[174:177], v[78:81], v[82:85]
	v_mfma_f32_16x16x32_bf16 v[106:109], v[154:157], v[78:81], v[106:109]
	ds_read_b128 v[78:81], v170 offset:192
	s_nop 0
	ds_read_b128 v[82:85], v170 offset:8896
	ds_read_b128 v[148:151], v170 offset:17600
	ds_read_b128 v[154:157], v170 offset:26304
	s_waitcnt lgkmcnt(7)
	v_mfma_f32_16x16x32_bf16 v[142:145], v[160:163], v[54:57], v[142:145]
	v_mfma_f32_16x16x32_bf16 v[86:89], v[160:163], v[74:77], v[86:89]
	s_waitcnt lgkmcnt(6)
	v_mfma_f32_16x16x32_bf16 v[90:93], v[186:189], v[54:57], v[90:93]
	v_mfma_f32_16x16x32_bf16 v[94:97], v[186:189], v[74:77], v[94:97]
	s_waitcnt lgkmcnt(5)
	v_mfma_f32_16x16x32_bf16 v[98:101], v[190:193], v[54:57], v[98:101]
	s_waitcnt lgkmcnt(4)
	v_mfma_f32_16x16x32_bf16 v[54:57], v[194:197], v[54:57], v[62:65]
	v_mfma_f32_16x16x32_bf16 v[62:65], v[194:197], v[74:77], v[70:73]
	v_mfma_f32_16x16x32_bf16 v[106:109], v[190:193], v[74:77], v[106:109]
	s_nop 1
	ds_read_b128 v[70:73], v170 offset:256
	ds_read_b128 v[74:77], v170 offset:8960
	ds_read_b128 v[160:163], v170 offset:17664
	ds_read_b128 v[174:177], v170 offset:26368
	s_waitcnt lgkmcnt(7)
	v_mfma_f32_16x16x32_bf16 v[142:145], v[78:81], v[46:49], v[142:145]
	v_mfma_f32_16x16x32_bf16 v[78:81], v[78:81], v[66:69], v[86:89]
	s_waitcnt lgkmcnt(6)
	v_mfma_f32_16x16x32_bf16 v[86:89], v[82:85], v[46:49], v[90:93]
	v_mfma_f32_16x16x32_bf16 v[82:85], v[82:85], v[66:69], v[94:97]
	s_waitcnt lgkmcnt(5)
	v_mfma_f32_16x16x32_bf16 v[90:93], v[148:151], v[46:49], v[98:101]
	v_mfma_f32_16x16x32_bf16 v[94:97], v[148:151], v[66:69], v[106:109]
	s_waitcnt lgkmcnt(4)
	v_mfma_f32_16x16x32_bf16 v[46:49], v[154:157], v[46:49], v[54:57]
	v_mfma_f32_16x16x32_bf16 v[54:57], v[154:157], v[66:69], v[62:65]
	s_nop 2
	ds_read_b128 v[62:65], v170 offset:320
	ds_read_b128 v[66:69], v170 offset:9024
	ds_read_b128 v[98:101], v170 offset:17728
	ds_read_b128 v[106:109], v170 offset:26432
	s_waitcnt lgkmcnt(7)
	v_mfma_f32_16x16x32_bf16 v[142:145], v[70:73], v[34:37], v[142:145]
	v_mfma_f32_16x16x32_bf16 v[70:73], v[70:73], v[58:61], v[78:81]
	s_waitcnt lgkmcnt(6)
	v_mfma_f32_16x16x32_bf16 v[78:81], v[74:77], v[34:37], v[86:89]
	v_mfma_f32_16x16x32_bf16 v[74:77], v[74:77], v[58:61], v[82:85]
	s_waitcnt lgkmcnt(5)
	v_mfma_f32_16x16x32_bf16 v[82:85], v[160:163], v[34:37], v[90:93]
	v_mfma_f32_16x16x32_bf16 v[86:89], v[160:163], v[58:61], v[94:97]
	s_waitcnt lgkmcnt(4)
	v_mfma_f32_16x16x32_bf16 v[34:37], v[174:177], v[34:37], v[46:49]
	v_mfma_f32_16x16x32_bf16 v[46:49], v[174:177], v[58:61], v[54:57]
	s_nop 2
	ds_read_b128 v[54:57], v170 offset:384
	ds_read_b128 v[58:61], v170 offset:9088
	ds_read_b128 v[90:93], v170 offset:17792
	ds_read_b128 v[94:97], v170 offset:26496
	s_waitcnt lgkmcnt(7)
	v_mfma_f32_16x16x32_bf16 v[142:145], v[62:65], v[30:33], v[142:145]
	v_mfma_f32_16x16x32_bf16 v[62:65], v[62:65], v[50:53], v[70:73]
	s_waitcnt lgkmcnt(6)
	v_mfma_f32_16x16x32_bf16 v[70:73], v[66:69], v[30:33], v[78:81]
	v_mfma_f32_16x16x32_bf16 v[66:69], v[66:69], v[50:53], v[74:77]
	s_waitcnt lgkmcnt(5)
	v_mfma_f32_16x16x32_bf16 v[74:77], v[98:101], v[30:33], v[82:85]
	v_mfma_f32_16x16x32_bf16 v[78:81], v[98:101], v[50:53], v[86:89]
	s_waitcnt lgkmcnt(4)
	v_mfma_f32_16x16x32_bf16 v[30:33], v[106:109], v[30:33], v[34:37]
	v_mfma_f32_16x16x32_bf16 v[34:37], v[106:109], v[50:53], v[46:49]
	s_nop 2
	ds_read_b128 v[46:49], v170 offset:448
	ds_read_b128 v[50:53], v170 offset:9152
	ds_read_b128 v[82:85], v170 offset:17856
	ds_read_b128 v[86:89], v170 offset:26560
	s_waitcnt lgkmcnt(7)
	v_mfma_f32_16x16x32_bf16 v[98:101], v[54:57], v[26:29], v[142:145]
	v_mfma_f32_16x16x32_bf16 v[54:57], v[54:57], v[42:45], v[62:65]
	s_waitcnt lgkmcnt(6)
	v_mfma_f32_16x16x32_bf16 v[62:65], v[58:61], v[26:29], v[70:73]
	v_mfma_f32_16x16x32_bf16 v[58:61], v[58:61], v[42:45], v[66:69]
	s_waitcnt lgkmcnt(5)
; __device__ __forceinline__ float bf_lo(unsigned w) { return __uint_as_float(w << 16); }
; __device__ __forceinline__ float bf_hi(unsigned w) { return __uint_as_float(w & 0xffff0000u); }
; __device__ __forceinline__ float sigmoidf_(float x) { return fast_rcp(1.0f + fast_exp(-x)); }
; __device__ __forceinline__ void lru_fused(const bf16* XC, const bf16* Wrg_t, const bf16* PROJ, bf16* YL, const float* b_a, const float* b_x, const float* sp8,
;                                           LAS unsigned char* lds, int tid, int lane, int wave, int vcu, int G) {
;     ...
;             { const size_t rown = (i + 1 < SEQ / 256) ? row0 + 256 : row0;
; #pragma unroll
;                 for (int r2 = 0; r2 < 2; ++r2) { const size_t ro = (rown + 16 * r2 + fr) * D, rg = (rown + 16 * r2 + fr) * NIN;
; #pragma unroll
;                     for (int kb = 0; kb < 8; ++kb) af[r2][kb] = *(const bf16x8*)(abase + ro + 32 * kb);
; #pragma unroll
;                     for (int c2 = 0; c2 < 2; ++c2) { xqn[r2][c2] = *(const v2u*)(xbase + ro + 16 * c2); gqn[r2][c2] = *(const v2u*)(gbase + rg + 16 * c2); } } }
;             float A[2][2][4], U[2][2][4];
; #pragma unroll
;             for (int r2 = 0; r2 < 2; ++r2)
; #pragma unroll
;                 for (int c2 = 0; c2 < 2; ++c2) { const f32x4 rp = acc[r2][c2] + ba[c2], ip = acc[r2][c2 + 2] + bx[c2]; const v2u xw = xq[r2][c2];
;                     const float xv[4] = {bf_lo(xw.x), bf_hi(xw.x), bf_lo(xw.y), bf_hi(xw.y)};
; #pragma unroll
;                     for (int j = 0; j < 4; ++j) { const float r = pg8::sigmoidf_(rp[j]), ig = pg8::sigmoidf_(ip[j]);
;                         const float av = __builtin_amdgcn_exp2f(sp[c2][j] * r);
;                         A[r2][c2][j] = av; U[r2][c2][j] = __builtin_amdgcn_sqrtf(fmaxf(__builtin_fmaf(-av, av, 1.0f), 0.0f)) * (ig * xv[j]); } }
	v_mfma_f32_16x16x32_bf16 v[66:69], v[90:93], v[26:29], v[74:77]
	v_mfma_f32_16x16x32_bf16 v[70:73], v[90:93], v[42:45], v[78:81]
	s_waitcnt lgkmcnt(4)
	v_mfma_f32_16x16x32_bf16 v[26:29], v[94:97], v[26:29], v[30:33]
	v_mfma_f32_16x16x32_bf16 v[30:33], v[94:97], v[42:45], v[34:37]
	s_waitcnt lgkmcnt(3)
	v_mfma_f32_16x16x32_bf16 v[106:109], v[46:49], v[22:25], v[98:101]
	v_mfma_f32_16x16x32_bf16 v[98:101], v[46:49], v[38:41], v[54:57]
	s_waitcnt lgkmcnt(2)
	v_mfma_f32_16x16x32_bf16 v[188:191], v[50:53], v[22:25], v[62:65]
	v_mfma_f32_16x16x32_bf16 v[90:93], v[50:53], v[38:41], v[58:61]
	s_waitcnt lgkmcnt(1)
	v_mfma_f32_16x16x32_bf16 v[182:185], v[82:85], v[22:25], v[66:69]
	v_mfma_f32_16x16x32_bf16 v[94:97], v[82:85], v[38:41], v[70:73]
	s_waitcnt lgkmcnt(0)
	v_mfma_f32_16x16x32_bf16 v[192:195], v[86:89], v[22:25], v[26:29]
	v_mfma_f32_16x16x32_bf16 v[86:89], v[86:89], v[38:41], v[30:33]
	v_add_f32_e32 v3, v6, v106
	v_mul_f32_e32 v3, 0xbfb8aa3b, v3
	v_exp_f32_e32 v3, v3
	s_add_u32 s23, s19, 0xffffff00
	s_addc_u32 s24, s20, -1
	s_cmp_eq_u32 s64, 0x3e00000
	s_cselect_b32 s25, s24, s20
	s_cselect_b32 s24, s23, s19
	v_mov_b32_e32 v39, s25
	v_or_b32_e32 v38, s24, v110
	v_lshlrev_b64 v[40:41], 13, v[38:39]
	v_mad_u64_u32 v[38:39], s[26:27], v38, s13, v[126:127]
	s_mul_i32 s23, s25, 0xa000
	v_lshl_add_u64 v[22:23], v[122:123], 0, v[40:41]
	v_lshl_add_u64 v[40:41], v[124:125], 0, v[40:41]
	v_add_u32_e32 v39, s23, v39
	global_load_dwordx4 v[70:73], v[22:23], off
	s_nop 0
	v_add_f32_e32 v173, v14, v182
	v_mul_f32_e32 v173, 0xbfb8aa3b, v173
	v_exp_f32_e32 v174, v173
	v_add_f32_e32 v3, 1.0, v3
	v_rcp_f32_e32 v3, v3
	v_add_f32_e32 v107, v7, v107
	v_add_f32_e32 v174, 1.0, v174
	v_mul_f32_e32 v107, 0xbfb8aa3b, v107
	v_mul_f32_e32 v3, v134, v3
	v_exp_f32_e32 v173, v3
	v_rcp_f32_e32 v174, v174
	v_exp_f32_e32 v107, v107
	v_lshlrev_b32_e32 v106, 16, v198
	v_fma_f32 v175, -v173, v173, 1.0
	global_load_dwordx4 v[62:65], v[22:23], off offset:64
	v_mul_f32_e32 v106, v174, v106
	v_add_f32_e32 v174, v15, v183
	v_add_f32_e32 v107, 1.0, v107
	v_max_f32_e32 v175, 0, v175
	v_mul_f32_e32 v174, 0xbfb8aa3b, v174
	v_rcp_f32_e32 v107, v107
	v_sqrt_f32_e32 v175, v175
	v_exp_f32_e32 v174, v174
	v_add_f32_e32 v177, v16, v184
	v_mul_f32_e32 v107, v135, v107
	v_mul_f32_e32 v175, v106, v175
	v_add_f32_e32 v106, 1.0, v174
	v_exp_f32_e32 v174, v107
	v_add_f32_e32 v107, v8, v108
	v_mul_f32_e32 v107, 0xbfb8aa3b, v107
	v_exp_f32_e32 v107, v107
	global_load_dwordx4 v[54:57], v[22:23], off offset:128
	v_fma_f32 v108, -v174, v174, 1.0
	v_rcp_f32_e32 v106, v106
	v_max_f32_e32 v108, 0, v108
	v_add_f32_e32 v107, 1.0, v107
	v_mul_f32_e32 v177, 0xbfb8aa3b, v177
	v_rcp_f32_e32 v107, v107
	v_sqrt_f32_e32 v108, v108
	v_exp_f32_e32 v181, v177
	v_and_b32_e32 v176, 0xffff0000, v198
	v_mul_f32_e32 v106, v106, v176
	v_mul_f32_e32 v107, v132, v107
	v_mul_f32_e32 v177, v106, v108
	v_add_f32_e32 v106, 1.0, v181
	v_exp_f32_e32 v181, v107
	v_add_f32_e32 v107, v9, v109
	global_load_dwordx4 v[46:49], v[22:23], off offset:192
	v_mul_f32_e32 v107, 0xbfb8aa3b, v107
	v_exp_f32_e32 v107, v107
	v_add_f32_e32 v109, v17, v185
	v_mul_f32_e32 v109, 0xbfb8aa3b, v109
	v_exp_f32_e32 v109, v109
	v_add_f32_e32 v107, 1.0, v107
	v_rcp_f32_e32 v107, v107
	v_fma_f32 v108, -v181, v181, 1.0
	v_max_f32_e32 v108, 0, v108
	v_and_b32_e32 v3, 0xffff0000, v199
	v_mul_f32_e32 v107, v133, v107
	v_exp_f32_e32 v176, v107
	v_sqrt_f32_e32 v107, v108
	v_add_f32_e32 v108, 1.0, v109
	v_rcp_f32_e32 v108, v108
	global_load_dwordx4 v[34:37], v[22:23], off offset:256
	v_fma_f32 v109, -v176, v176, 1.0
	v_max_f32_e32 v109, 0, v109
	v_sqrt_f32_e32 v109, v109
	v_mul_f32_e32 v3, v108, v3
	v_add_f32_e32 v108, v18, v192
	v_rcp_f32_e32 v106, v106
	v_mul_f32_e32 v182, v3, v109
	v_add_f32_e32 v3, v10, v188
	v_mul_f32_e32 v3, 0xbfb8aa3b, v3
	v_exp_f32_e32 v3, v3
	v_mul_f32_e32 v108, 0xbfb8aa3b, v108
	v_exp_f32_e32 v108, v108
	v_lshlrev_b32_e32 v186, 16, v199
	v_add_f32_e32 v3, 1.0, v3
	v_rcp_f32_e32 v3, v3
	v_mul_f32_e32 v106, v106, v186
	global_load_dwordx4 v[30:33], v[22:23], off offset:320
	v_mul_f32_e32 v184, v106, v107
	v_lshlrev_b32_e32 v107, 16, v105
	v_mul_f32_e32 v3, v138, v3
	v_exp_f32_e32 v183, v3
	v_and_b32_e32 v3, 0xffff0000, v105
	v_add_f32_e32 v105, 1.0, v108
	v_rcp_f32_e32 v105, v105
	v_lshlrev_b32_e32 v106, 16, v104
	v_fma_f32 v108, -v183, v183, 1.0
	v_add_f32_e32 v109, v19, v193
	v_mul_f32_e32 v105, v105, v106
	v_add_f32_e32 v106, v11, v189
	v_mul_f32_e32 v106, 0xbfb8aa3b, v106
	v_exp_f32_e32 v106, v106
	v_max_f32_e32 v108, 0, v108
	global_load_dwordx4 v[26:29], v[22:23], off offset:384
	v_mul_f32_e32 v109, 0xbfb8aa3b, v109
	v_sqrt_f32_e32 v108, v108
	v_add_f32_e32 v106, 1.0, v106
	v_rcp_f32_e32 v106, v106
	v_exp_f32_e32 v109, v109
	v_mul_f32_e32 v186, v105, v108
	v_and_b32_e32 v104, 0xffff0000, v104
	v_mul_f32_e32 v106, v139, v106
	v_exp_f32_e32 v185, v106
	v_add_f32_e32 v106, v12, v190
	v_mul_f32_e32 v106, 0xbfb8aa3b, v106
	v_exp_f32_e32 v106, v106
	v_add_f32_e32 v105, 1.0, v109
	v_rcp_f32_e32 v105, v105
	v_fma_f32 v108, -v185, v185, 1.0
	s_nop 0
	global_load_dwordx4 v[22:25], v[22:23], off offset:448
	v_add_f32_e32 v106, 1.0, v106
	v_rcp_f32_e32 v106, v106
	v_mul_f32_e32 v104, v105, v104
	v_max_f32_e32 v108, 0, v108
	v_sqrt_f32_e32 v108, v108
	v_mul_f32_e32 v105, v136, v106
	v_exp_f32_e32 v189, v105
	v_add_f32_e32 v105, v13, v191
	v_mul_f32_e32 v105, 0xbfb8aa3b, v105
	v_exp_f32_e32 v105, v105
	v_mul_f32_e32 v188, v104, v108
	v_add_f32_e32 v108, v21, v195
	v_mul_f32_e32 v108, 0xbfb8aa3b, v108
	v_add_f32_e32 v105, 1.0, v105
	v_rcp_f32_e32 v105, v105
	s_nop 0
	global_load_dwordx2 v[142:143], v[40:41], off
	v_exp_f32_e32 v108, v108
; __device__ __forceinline__ float bf_lo(unsigned w) { return __uint_as_float(w << 16); }
; __device__ __forceinline__ float bf_hi(unsigned w) { return __uint_as_float(w & 0xffff0000u); }
; __device__ __forceinline__ float sigmoidf_(float x) { return fast_rcp(1.0f + fast_exp(-x)); }
; __device__ __forceinline__ void lru_fused(const bf16* XC, const bf16* Wrg_t, const bf16* PROJ, bf16* YL, const float* b_a, const float* b_x, const float* sp8,
;                                           LAS unsigned char* lds, int tid, int lane, int wave, int vcu, int G) {
;     ...
;             { const size_t rown = (i + 1 < SEQ / 256) ? row0 + 256 : row0;
; #pragma unroll
;                 for (int r2 = 0; r2 < 2; ++r2) { const size_t ro = (rown + 16 * r2 + fr) * D, rg = (rown + 16 * r2 + fr) * NIN;
; #pragma unroll
;                     for (int kb = 0; kb < 8; ++kb) af[r2][kb] = *(const bf16x8*)(abase + ro + 32 * kb);
; #pragma unroll
;                     for (int c2 = 0; c2 < 2; ++c2) { xqn[r2][c2] = *(const v2u*)(xbase + ro + 16 * c2); gqn[r2][c2] = *(const v2u*)(gbase + rg + 16 * c2); } } }
;             float A[2][2][4], U[2][2][4];
; #pragma unroll
;             for (int r2 = 0; r2 < 2; ++r2)
; #pragma unroll
;                 for (int c2 = 0; c2 < 2; ++c2) { const f32x4 rp = acc[r2][c2] + ba[c2], ip = acc[r2][c2 + 2] + bx[c2]; const v2u xw = xq[r2][c2];
;                     const float xv[4] = {bf_lo(xw.x), bf_hi(xw.x), bf_lo(xw.y), bf_hi(xw.y)};
; #pragma unroll
;                     for (int j = 0; j < 4; ++j) { const float r = pg8::sigmoidf_(rp[j]), ig = pg8::sigmoidf_(ip[j]);
;                         const float av = __builtin_amdgcn_exp2f(sp[c2][j] * r);
;                         A[r2][c2][j] = av; U[r2][c2][j] = __builtin_amdgcn_sqrtf(fmaxf(__builtin_fmaf(-av, av, 1.0f), 0.0f)) * (ig * xv[j]); } }
	v_fma_f32 v106, -v189, v189, 1.0
	v_max_f32_e32 v106, 0, v106
	v_mul_f32_e32 v105, v137, v105
	v_exp_f32_e32 v187, v105
	v_sqrt_f32_e32 v105, v106
	v_add_f32_e32 v106, 1.0, v108
	v_rcp_f32_e32 v106, v106
	v_fma_f32 v108, -v187, v187, 1.0
	v_max_f32_e32 v108, 0, v108
	v_sqrt_f32_e32 v108, v108
	v_mul_f32_e32 v3, v106, v3
	v_add_f32_e32 v109, v20, v194
	v_mul_f32_e32 v109, 0xbfb8aa3b, v109
	v_mul_f32_e32 v190, v3, v108
	v_add_f32_e32 v3, v6, v98
	global_load_dwordx2 v[144:145], v[40:41], off offset:32
	v_mul_f32_e32 v3, 0xbfb8aa3b, v3
	v_exp_f32_e32 v3, v3
	v_exp_f32_e32 v109, v109
	v_add_f32_e32 v99, v7, v99
	v_mul_f32_e32 v99, 0xbfb8aa3b, v99
	v_add_f32_e32 v3, 1.0, v3
	v_rcp_f32_e32 v3, v3
	v_exp_f32_e32 v99, v99
	v_add_f32_e32 v104, 1.0, v109
	v_add_f32_e32 v94, v14, v94
	v_rcp_f32_e32 v104, v104
	v_mul_f32_e32 v94, 0xbfb8aa3b, v94
	v_mul_f32_e32 v3, v134, v3
	v_exp_f32_e32 v94, v94
	v_exp_f32_e32 v98, v3
	global_load_dwordx2 v[154:155], v[38:39], off
	v_add_f32_e32 v99, 1.0, v99
	v_add_f32_e32 v101, v9, v101
	v_rcp_f32_e32 v99, v99
	v_mul_f32_e32 v101, 0xbfb8aa3b, v101
	v_exp_f32_e32 v101, v101
	v_mul_f32_e32 v104, v104, v107
	v_mul_f32_e32 v191, v104, v105
	v_lshlrev_b32_e32 v105, 16, v103
	v_and_b32_e32 v3, 0xffff0000, v103
	v_add_f32_e32 v94, 1.0, v94
	v_fma_f32 v103, -v98, v98, 1.0
	v_add_f32_e32 v95, v15, v95
	v_rcp_f32_e32 v94, v94
	v_max_f32_e32 v103, 0, v103
	v_mul_f32_e32 v95, 0xbfb8aa3b, v95
	global_load_dwordx2 v[156:157], v[38:39], off offset:32
	v_mul_f32_e32 v99, v135, v99
	v_sqrt_f32_e32 v103, v103
	v_exp_f32_e32 v95, v95
	v_exp_f32_e32 v99, v99
	v_add_f32_e32 v100, v8, v100
	v_add_f32_e32 v101, 1.0, v101
	v_mul_f32_e32 v100, 0xbfb8aa3b, v100
	v_rcp_f32_e32 v101, v101
	v_lshlrev_b32_e32 v104, 16, v102
	v_exp_f32_e32 v100, v100
	v_mul_f32_e32 v94, v94, v104
	v_mul_f32_e32 v94, v94, v103
	v_add_f32_e32 v95, 1.0, v95
	v_fma_f32 v103, -v99, v99, 1.0
	v_add_f32_e32 v97, v17, v97
	v_rcp_f32_e32 v95, v95
	v_lshl_add_u64 v[38:39], v[110:111], 0, s[24:25]
	v_lshl_add_u64 v[148:149], v[38:39], 0, 16
	v_lshlrev_b64 v[150:151], 13, v[148:149]
	v_lshl_add_u64 v[38:39], v[122:123], 0, v[150:151]
	global_load_dwordx4 v[82:85], v[38:39], off
	v_max_f32_e32 v103, 0, v103
	v_mul_f32_e32 v97, 0xbfb8aa3b, v97
	v_mul_f32_e32 v101, v133, v101
	v_sqrt_f32_e32 v103, v103
	v_add_f32_e32 v100, 1.0, v100
	v_exp_f32_e32 v97, v97
	v_exp_f32_e32 v101, v101
	v_rcp_f32_e32 v100, v100
	v_and_b32_e32 v102, 0xffff0000, v102
	v_mul_f32_e32 v95, v95, v102
	v_add_f32_e32 v96, v16, v96
	v_mul_f32_e32 v95, v95, v103
	v_add_f32_e32 v97, 1.0, v97
	v_fma_f32 v103, -v101, v101, 1.0
	v_mul_f32_e32 v96, 0xbfb8aa3b, v96
	global_load_dwordx4 v[78:81], v[38:39], off offset:64
	v_mul_f32_e32 v100, v132, v100
	v_rcp_f32_e32 v97, v97
	v_max_f32_e32 v103, 0, v103
	v_exp_f32_e32 v96, v96
	v_exp_f32_e32 v100, v100
	v_sqrt_f32_e32 v103, v103
	v_mul_f32_e32 v3, v97, v3
	v_add_f32_e32 v96, 1.0, v96
	v_fma_f32 v102, -v100, v100, 1.0
	v_mul_f32_e32 v97, v3, v103
	v_add_f32_e32 v3, v10, v90
	v_rcp_f32_e32 v96, v96
	v_max_f32_e32 v102, 0, v102
	v_mul_f32_e32 v3, 0xbfb8aa3b, v3
	v_sqrt_f32_e32 v102, v102
	global_load_dwordx4 v[74:77], v[38:39], off offset:128
	v_exp_f32_e32 v3, v3
	v_mul_f32_e32 v96, v96, v105
	v_lshlrev_b32_e32 v90, 16, v4
	v_mul_f32_e32 v96, v96, v102
	v_and_b32_e32 v102, 0xffff0000, v4
	v_add_f32_e32 v3, 1.0, v3
	v_add_f32_e32 v4, v18, v86
	v_rcp_f32_e32 v3, v3
	v_mul_f32_e32 v4, 0xbfb8aa3b, v4
	v_exp_f32_e32 v86, v4
	v_lshlrev_b32_e32 v103, 16, v5
	v_mul_f32_e32 v3, v138, v3
	v_exp_f32_e32 v4, v3
	v_and_b32_e32 v3, 0xffff0000, v5
	v_add_f32_e32 v5, 1.0, v86
	v_rcp_f32_e32 v5, v5
	global_load_dwordx4 v[66:69], v[38:39], off offset:192
	v_fma_f32 v86, -v4, v4, 1.0
	v_add_f32_e32 v87, v19, v87
	v_max_f32_e32 v86, 0, v86
	v_mul_f32_e32 v5, v5, v90
	v_add_f32_e32 v90, v11, v91
	v_mul_f32_e32 v90, 0xbfb8aa3b, v90
	v_exp_f32_e32 v90, v90
	v_mul_f32_e32 v87, 0xbfb8aa3b, v87
	v_sqrt_f32_e32 v86, v86
	v_exp_f32_e32 v87, v87
	v_add_f32_e32 v90, 1.0, v90
; __device__ __forceinline__ float bf_lo(unsigned w) { return __uint_as_float(w << 16); }
; __device__ __forceinline__ float bf_hi(unsigned w) { return __uint_as_float(w & 0xffff0000u); }
; __device__ __forceinline__ float sigmoidf_(float x) { return fast_rcp(1.0f + fast_exp(-x)); }
; __device__ __forceinline__ void lru_fused(const bf16* XC, const bf16* Wrg_t, const bf16* PROJ, bf16* YL, const float* b_a, const float* b_x, const float* sp8,
;                                           LAS unsigned char* lds, int tid, int lane, int wave, int vcu, int G) {
;     ...
;                 for (int c2 = 0; c2 < 2; ++c2) { const f32x4 rp = acc[r2][c2] + ba[c2], ip = acc[r2][c2 + 2] + bx[c2]; const v2u xw = xq[r2][c2];
;                     const float xv[4] = {bf_lo(xw.x), bf_hi(xw.x), bf_lo(xw.y), bf_hi(xw.y)};
; #pragma unroll
;                     for (int j = 0; j < 4; ++j) { const float r = pg8::sigmoidf_(rp[j]), ig = pg8::sigmoidf_(ip[j]);
;                         const float av = __builtin_amdgcn_exp2f(sp[c2][j] * r);
;                         A[r2][c2][j] = av; U[r2][c2][j] = __builtin_amdgcn_sqrtf(fmaxf(__builtin_fmaf(-av, av, 1.0f), 0.0f)) * (ig * xv[j]); } }
;     ...
; #pragma unroll
;             for (int r2 = 0; r2 < 2; ++r2)
; #pragma unroll
;                 for (int c2 = 0; c2 < 2; ++c2)
;                     asm volatile("s_nop 1\n\t" LRU_STEP(1) LRU_STEP(2) LRU_STEP(4) LRU_STEP(8)
;                                  : "+v"(A[r2][c2][0]), "+v"(A[r2][c2][1]), "+v"(A[r2][c2][2]), "+v"(A[r2][c2][3]), "+v"(U[r2][c2][0]), "+v"(U[r2][c2][1]), "+v"(U[r2][c2][2]), "+v"(U[r2][c2][3]));
	v_rcp_f32_e32 v90, v90
	v_mul_f32_e32 v86, v5, v86
	v_add_f32_e32 v5, 1.0, v87
	v_rcp_f32_e32 v87, v5
	global_load_dwordx4 v[58:61], v[38:39], off offset:256
	v_mul_f32_e32 v5, v139, v90
	v_add_f32_e32 v90, v12, v92
	v_mul_f32_e32 v90, 0xbfb8aa3b, v90
	v_exp_f32_e32 v90, v90
	v_exp_f32_e32 v5, v5
	v_add_f32_e32 v88, v20, v88
	v_add_f32_e32 v89, v21, v89
	v_add_f32_e32 v90, 1.0, v90
	v_rcp_f32_e32 v90, v90
	v_fma_f32 v91, -v5, v5, 1.0
	v_max_f32_e32 v91, 0, v91
	v_sqrt_f32_e32 v91, v91
	v_mul_f32_e32 v90, v136, v90
	v_exp_f32_e32 v92, v90
	v_add_f32_e32 v90, v13, v93
	global_load_dwordx4 v[50:53], v[38:39], off offset:320
	v_mul_f32_e32 v90, 0xbfb8aa3b, v90
	v_exp_f32_e32 v90, v90
	v_mul_f32_e32 v88, 0xbfb8aa3b, v88
	v_mul_f32_e32 v89, 0xbfb8aa3b, v89
	v_exp_f32_e32 v88, v88
	v_add_f32_e32 v90, 1.0, v90
	v_rcp_f32_e32 v90, v90
	v_exp_f32_e32 v89, v89
	v_mul_f32_e32 v87, v87, v102
	v_mul_f32_e32 v87, v87, v91
	v_mul_f32_e32 v90, v137, v90
	v_exp_f32_e32 v93, v90
	v_fma_f32 v91, -v92, v92, 1.0
	v_max_f32_e32 v91, 0, v91
	v_add_f32_e32 v88, 1.0, v88
	global_load_dwordx4 v[42:45], v[38:39], off offset:384
	v_sqrt_f32_e32 v90, v91
	v_add_f32_e32 v89, 1.0, v89
	v_fma_f32 v91, -v93, v93, 1.0
	v_rcp_f32_e32 v88, v88
	v_rcp_f32_e32 v89, v89
	v_max_f32_e32 v91, 0, v91
	v_sqrt_f32_e32 v91, v91
	v_mul_f32_e32 v88, v88, v103
	v_mul_f32_e32 v3, v89, v3
	v_mul_f32_e32 v88, v88, v90
	v_mul_f32_e32 v89, v3, v91
	s_nop 1
	v_fmac_f32_dpp v175, v175, v173 row_shr:1 row_mask:0xf bank_mask:0xf
	v_mul_f32_dpp v173, v173, v173 row_shr:1 row_mask:0xf bank_mask:0xf
	v_fmac_f32_dpp v177, v177, v174 row_shr:1 row_mask:0xf bank_mask:0xf
	v_mul_f32_dpp v174, v174, v174 row_shr:1 row_mask:0xf bank_mask:0xf
	s_nop 0
	global_load_dwordx4 v[38:41], v[38:39], off offset:448
	v_fmac_f32_dpp v184, v184, v181 row_shr:1 row_mask:0xf bank_mask:0xf
	v_mul_f32_dpp v181, v181, v181 row_shr:1 row_mask:0xf bank_mask:0xf
	v_fmac_f32_dpp v182, v182, v176 row_shr:1 row_mask:0xf bank_mask:0xf
	v_mul_f32_dpp v176, v176, v176 row_shr:1 row_mask:0xf bank_mask:0xf
	v_fmac_f32_dpp v175, v175, v173 row_shr:2 row_mask:0xf bank_mask:0xf
	v_mul_f32_dpp v173, v173, v173 row_shr:2 row_mask:0xf bank_mask:0xf
	v_fmac_f32_dpp v177, v177, v174 row_shr:2 row_mask:0xf bank_mask:0xf
	v_mul_f32_dpp v174, v174, v174 row_shr:2 row_mask:0xf bank_mask:0xf
	v_fmac_f32_dpp v184, v184, v181 row_shr:2 row_mask:0xf bank_mask:0xf
	v_mul_f32_dpp v181, v181, v181 row_shr:2 row_mask:0xf bank_mask:0xf
	v_fmac_f32_dpp v182, v182, v176 row_shr:2 row_mask:0xf bank_mask:0xf
	v_mul_f32_dpp v176, v176, v176 row_shr:2 row_mask:0xf bank_mask:0xf
	v_fmac_f32_dpp v175, v175, v173 row_shr:4 row_mask:0xf bank_mask:0xf
	v_mul_f32_dpp v173, v173, v173 row_shr:4 row_mask:0xf bank_mask:0xf
	v_fmac_f32_dpp v177, v177, v174 row_shr:4 row_mask:0xf bank_mask:0xf
	v_mad_u64_u32 v[162:163], s[24:25], v148, s13, v[126:127]
	v_mov_b32_e32 v148, v163
	v_mad_u64_u32 v[148:149], s[24:25], v149, s13, v[148:149]
	v_lshl_add_u64 v[150:151], v[124:125], 0, v[150:151]
	v_mov_b32_e32 v163, v148
	global_load_dwordx2 v[148:149], v[150:151], off
	v_mul_f32_dpp v174, v174, v174 row_shr:4 row_mask:0xf bank_mask:0xf
	v_fmac_f32_dpp v184, v184, v181 row_shr:4 row_mask:0xf bank_mask:0xf
	v_mul_f32_dpp v181, v181, v181 row_shr:4 row_mask:0xf bank_mask:0xf
	v_fmac_f32_dpp v182, v182, v176 row_shr:4 row_mask:0xf bank_mask:0xf
	v_mul_f32_dpp v176, v176, v176 row_shr:4 row_mask:0xf bank_mask:0xf
	v_fmac_f32_dpp v175, v175, v173 row_shr:8 row_mask:0xf bank_mask:0xf
	v_mul_f32_dpp v173, v173, v173 row_shr:8 row_mask:0xf bank_mask:0xf
	v_fmac_f32_dpp v177, v177, v174 row_shr:8 row_mask:0xf bank_mask:0xf
	v_mul_f32_dpp v174, v174, v174 row_shr:8 row_mask:0xf bank_mask:0xf
	v_fmac_f32_dpp v184, v184, v181 row_shr:8 row_mask:0xf bank_mask:0xf
	v_mul_f32_dpp v181, v181, v181 row_shr:8 row_mask:0xf bank_mask:0xf
	v_fmac_f32_dpp v182, v182, v176 row_shr:8 row_mask:0xf bank_mask:0xf
	v_mul_f32_dpp v176, v176, v176 row_shr:8 row_mask:0xf bank_mask:0xf

; __device__ __forceinline__ void lru_fused(const bf16* XC, const bf16* Wrg_t, const bf16* PROJ, bf16* YL, const float* b_a, const float* b_x, const float* sp8,
;                                           LAS unsigned char* lds, int tid, int lane, int wave, int vcu, int G) {
;     ...
; #pragma unroll
;             for (int r2 = 0; r2 < 2; ++r2)
; #pragma unroll
;                 for (int c2 = 0; c2 < 2; ++c2)
;                     asm volatile("s_nop 1\n\t" LRU_STEP(1) LRU_STEP(2) LRU_STEP(4) LRU_STEP(8)
;                                  : "+v"(A[r2][c2][0]), "+v"(A[r2][c2][1]), "+v"(A[r2][c2][2]), "+v"(A[r2][c2][3]), "+v"(U[r2][c2][0]), "+v"(U[r2][c2][1]), "+v"(U[r2][c2][2]), "+v"(U[r2][c2][3]));
;     ...
;             const int l15 = (lane & 48) | 15;
; #pragma unroll
;             for (int c2 = 0; c2 < 2; ++c2)
; #pragma unroll
;                 for (int j = 0; j < 4; ++j) { const float a15 = __shfl(A[0][c2][j], l15), u15 = __shfl(U[0][c2][j], l15);
;                     U[1][c2][j] = A[1][c2][j] * u15 + U[1][c2][j]; A[1][c2][j] = A[1][c2][j] * a15; }
	ds_bpermute_b32 v90, v172, v173
	ds_bpermute_b32 v102, v172, v175
	global_load_dwordx2 v[160:161], v[162:163], off
	ds_bpermute_b32 v103, v172, v177
	ds_bpermute_b32 v91, v172, v174
	ds_bpermute_b32 v104, v172, v184
	ds_bpermute_b32 v105, v172, v182
	s_nop 1
	v_fmac_f32_dpp v186, v186, v183 row_shr:1 row_mask:0xf bank_mask:0xf
	v_mul_f32_dpp v183, v183, v183 row_shr:1 row_mask:0xf bank_mask:0xf
	v_fmac_f32_dpp v188, v188, v185 row_shr:1 row_mask:0xf bank_mask:0xf
	v_mul_f32_dpp v185, v185, v185 row_shr:1 row_mask:0xf bank_mask:0xf
	v_fmac_f32_dpp v191, v191, v189 row_shr:1 row_mask:0xf bank_mask:0xf
	v_mul_f32_dpp v189, v189, v189 row_shr:1 row_mask:0xf bank_mask:0xf
	v_fmac_f32_dpp v190, v190, v187 row_shr:1 row_mask:0xf bank_mask:0xf
	v_mul_f32_dpp v187, v187, v187 row_shr:1 row_mask:0xf bank_mask:0xf
	v_fmac_f32_dpp v186, v186, v183 row_shr:2 row_mask:0xf bank_mask:0xf
	v_mul_f32_dpp v183, v183, v183 row_shr:2 row_mask:0xf bank_mask:0xf
	v_fmac_f32_dpp v188, v188, v185 row_shr:2 row_mask:0xf bank_mask:0xf
	s_nop 0
	global_load_dwordx2 v[162:163], v[162:163], off offset:32
	v_mul_f32_dpp v185, v185, v185 row_shr:2 row_mask:0xf bank_mask:0xf
	v_fmac_f32_dpp v191, v191, v189 row_shr:2 row_mask:0xf bank_mask:0xf
	v_mul_f32_dpp v189, v189, v189 row_shr:2 row_mask:0xf bank_mask:0xf
	v_fmac_f32_dpp v190, v190, v187 row_shr:2 row_mask:0xf bank_mask:0xf
	v_mul_f32_dpp v187, v187, v187 row_shr:2 row_mask:0xf bank_mask:0xf
	v_fmac_f32_dpp v186, v186, v183 row_shr:4 row_mask:0xf bank_mask:0xf
	v_mul_f32_dpp v183, v183, v183 row_shr:4 row_mask:0xf bank_mask:0xf
	v_fmac_f32_dpp v188, v188, v185 row_shr:4 row_mask:0xf bank_mask:0xf
	v_mul_f32_dpp v185, v185, v185 row_shr:4 row_mask:0xf bank_mask:0xf
	v_fmac_f32_dpp v191, v191, v189 row_shr:4 row_mask:0xf bank_mask:0xf
	v_mul_f32_dpp v189, v189, v189 row_shr:4 row_mask:0xf bank_mask:0xf
	v_fmac_f32_dpp v190, v190, v187 row_shr:4 row_mask:0xf bank_mask:0xf
	v_mul_f32_dpp v187, v187, v187 row_shr:4 row_mask:0xf bank_mask:0xf
	v_fmac_f32_dpp v186, v186, v183 row_shr:8 row_mask:0xf bank_mask:0xf
	v_mul_f32_dpp v183, v183, v183 row_shr:8 row_mask:0xf bank_mask:0xf
	s_nop 0
	global_load_dwordx2 v[150:151], v[150:151], off offset:32
	v_fmac_f32_dpp v188, v188, v185 row_shr:8 row_mask:0xf bank_mask:0xf
	v_mul_f32_dpp v185, v185, v185 row_shr:8 row_mask:0xf bank_mask:0xf
	v_fmac_f32_dpp v191, v191, v189 row_shr:8 row_mask:0xf bank_mask:0xf
	v_mul_f32_dpp v189, v189, v189 row_shr:8 row_mask:0xf bank_mask:0xf
	v_fmac_f32_dpp v190, v190, v187 row_shr:8 row_mask:0xf bank_mask:0xf
	v_mul_f32_dpp v187, v187, v187 row_shr:8 row_mask:0xf bank_mask:0xf

; __device__ __forceinline__ void lru_fused(const bf16* XC, const bf16* Wrg_t, const bf16* PROJ, bf16* YL, const float* b_a, const float* b_x, const float* sp8,
;                                           LAS unsigned char* lds, int tid, int lane, int wave, int vcu, int G) {
;     ...
; #pragma unroll
;             for (int r2 = 0; r2 < 2; ++r2)
; #pragma unroll
;                 for (int c2 = 0; c2 < 2; ++c2)
;                     asm volatile("s_nop 1\n\t" LRU_STEP(1) LRU_STEP(2) LRU_STEP(4) LRU_STEP(8)
;                                  : "+v"(A[r2][c2][0]), "+v"(A[r2][c2][1]), "+v"(A[r2][c2][2]), "+v"(A[r2][c2][3]), "+v"(U[r2][c2][0]), "+v"(U[r2][c2][1]), "+v"(U[r2][c2][2]), "+v"(U[r2][c2][3]));
	s_nop 1
	v_fmac_f32_dpp v94, v94, v98 row_shr:1 row_mask:0xf bank_mask:0xf
	v_mul_f32_dpp v98, v98, v98 row_shr:1 row_mask:0xf bank_mask:0xf
	v_fmac_f32_dpp v95, v95, v99 row_shr:1 row_mask:0xf bank_mask:0xf
	v_mul_f32_dpp v99, v99, v99 row_shr:1 row_mask:0xf bank_mask:0xf
	v_fmac_f32_dpp v96, v96, v100 row_shr:1 row_mask:0xf bank_mask:0xf
	v_mul_f32_dpp v100, v100, v100 row_shr:1 row_mask:0xf bank_mask:0xf
	v_fmac_f32_dpp v97, v97, v101 row_shr:1 row_mask:0xf bank_mask:0xf
	v_mul_f32_dpp v101, v101, v101 row_shr:1 row_mask:0xf bank_mask:0xf
	v_fmac_f32_dpp v94, v94, v98 row_shr:2 row_mask:0xf bank_mask:0xf
	v_mul_f32_dpp v98, v98, v98 row_shr:2 row_mask:0xf bank_mask:0xf
	v_fmac_f32_dpp v95, v95, v99 row_shr:2 row_mask:0xf bank_mask:0xf
	v_mul_f32_dpp v99, v99, v99 row_shr:2 row_mask:0xf bank_mask:0xf
	v_fmac_f32_dpp v96, v96, v100 row_shr:2 row_mask:0xf bank_mask:0xf
	v_mul_f32_dpp v100, v100, v100 row_shr:2 row_mask:0xf bank_mask:0xf
	v_fmac_f32_dpp v97, v97, v101 row_shr:2 row_mask:0xf bank_mask:0xf
	v_mul_f32_dpp v101, v101, v101 row_shr:2 row_mask:0xf bank_mask:0xf
	v_fmac_f32_dpp v94, v94, v98 row_shr:4 row_mask:0xf bank_mask:0xf
	v_mul_f32_dpp v98, v98, v98 row_shr:4 row_mask:0xf bank_mask:0xf
	v_fmac_f32_dpp v95, v95, v99 row_shr:4 row_mask:0xf bank_mask:0xf
	v_mul_f32_dpp v99, v99, v99 row_shr:4 row_mask:0xf bank_mask:0xf
	v_fmac_f32_dpp v96, v96, v100 row_shr:4 row_mask:0xf bank_mask:0xf
	v_mul_f32_dpp v100, v100, v100 row_shr:4 row_mask:0xf bank_mask:0xf
	v_fmac_f32_dpp v97, v97, v101 row_shr:4 row_mask:0xf bank_mask:0xf
	v_mul_f32_dpp v101, v101, v101 row_shr:4 row_mask:0xf bank_mask:0xf
	v_fmac_f32_dpp v94, v94, v98 row_shr:8 row_mask:0xf bank_mask:0xf
	v_mul_f32_dpp v98, v98, v98 row_shr:8 row_mask:0xf bank_mask:0xf
	v_fmac_f32_dpp v95, v95, v99 row_shr:8 row_mask:0xf bank_mask:0xf
	v_mul_f32_dpp v99, v99, v99 row_shr:8 row_mask:0xf bank_mask:0xf
	v_fmac_f32_dpp v96, v96, v100 row_shr:8 row_mask:0xf bank_mask:0xf
	v_mul_f32_dpp v100, v100, v100 row_shr:8 row_mask:0xf bank_mask:0xf
	v_fmac_f32_dpp v97, v97, v101 row_shr:8 row_mask:0xf bank_mask:0xf
	v_mul_f32_dpp v101, v101, v101 row_shr:8 row_mask:0xf bank_mask:0xf

; __device__ __forceinline__ void lru_fused(const bf16* XC, const bf16* Wrg_t, const bf16* PROJ, bf16* YL, const float* b_a, const float* b_x, const float* sp8,
;                                           LAS unsigned char* lds, int tid, int lane, int wave, int vcu, int G) {
;     ...
;             const int l15 = (lane & 48) | 15;
; #pragma unroll
;             for (int c2 = 0; c2 < 2; ++c2)
; #pragma unroll
;                 for (int j = 0; j < 4; ++j) { const float a15 = __shfl(A[0][c2][j], l15), u15 = __shfl(U[0][c2][j], l15);
;                     U[1][c2][j] = A[1][c2][j] * u15 + U[1][c2][j]; A[1][c2][j] = A[1][c2][j] * a15; }
	ds_bpermute_b32 v106, v172, v189
	s_waitcnt lgkmcnt(4)
	v_pk_fma_f32 v[94:95], v[98:99], v[102:103], v[94:95]
	s_waitcnt lgkmcnt(3)
	v_pk_mul_f32 v[98:99], v[98:99], v[90:91]
	ds_bpermute_b32 v90, v172, v181
	ds_bpermute_b32 v91, v172, v176
	s_waitcnt lgkmcnt(3)
	v_pk_fma_f32 v[96:97], v[100:101], v[104:105], v[96:97]
	ds_bpermute_b32 v102, v172, v183
	ds_bpermute_b32 v104, v172, v186
	ds_bpermute_b32 v103, v172, v185
	ds_bpermute_b32 v105, v172, v188
	ds_bpermute_b32 v108, v172, v191
	ds_bpermute_b32 v109, v172, v190
	ds_bpermute_b32 v107, v172, v187
	s_and_b32 s24, s22, 1
	s_nop 1
	v_fmac_f32_dpp v86, v86, v4 row_shr:1 row_mask:0xf bank_mask:0xf
	v_mul_f32_dpp v4, v4, v4 row_shr:1 row_mask:0xf bank_mask:0xf
	v_fmac_f32_dpp v87, v87, v5 row_shr:1 row_mask:0xf bank_mask:0xf
	v_mul_f32_dpp v5, v5, v5 row_shr:1 row_mask:0xf bank_mask:0xf
	v_fmac_f32_dpp v88, v88, v92 row_shr:1 row_mask:0xf bank_mask:0xf
	v_mul_f32_dpp v92, v92, v92 row_shr:1 row_mask:0xf bank_mask:0xf
	v_fmac_f32_dpp v89, v89, v93 row_shr:1 row_mask:0xf bank_mask:0xf
	v_mul_f32_dpp v93, v93, v93 row_shr:1 row_mask:0xf bank_mask:0xf
	v_fmac_f32_dpp v86, v86, v4 row_shr:2 row_mask:0xf bank_mask:0xf
	v_mul_f32_dpp v4, v4, v4 row_shr:2 row_mask:0xf bank_mask:0xf
	v_fmac_f32_dpp v87, v87, v5 row_shr:2 row_mask:0xf bank_mask:0xf
	v_mul_f32_dpp v5, v5, v5 row_shr:2 row_mask:0xf bank_mask:0xf
	v_fmac_f32_dpp v88, v88, v92 row_shr:2 row_mask:0xf bank_mask:0xf
	v_mul_f32_dpp v92, v92, v92 row_shr:2 row_mask:0xf bank_mask:0xf
	v_fmac_f32_dpp v89, v89, v93 row_shr:2 row_mask:0xf bank_mask:0xf
	v_mul_f32_dpp v93, v93, v93 row_shr:2 row_mask:0xf bank_mask:0xf
	v_fmac_f32_dpp v86, v86, v4 row_shr:4 row_mask:0xf bank_mask:0xf
	v_mul_f32_dpp v4, v4, v4 row_shr:4 row_mask:0xf bank_mask:0xf
	v_fmac_f32_dpp v87, v87, v5 row_shr:4 row_mask:0xf bank_mask:0xf
	v_mul_f32_dpp v5, v5, v5 row_shr:4 row_mask:0xf bank_mask:0xf
	v_fmac_f32_dpp v88, v88, v92 row_shr:4 row_mask:0xf bank_mask:0xf
	v_mul_f32_dpp v92, v92, v92 row_shr:4 row_mask:0xf bank_mask:0xf
	v_fmac_f32_dpp v89, v89, v93 row_shr:4 row_mask:0xf bank_mask:0xf
	v_mul_f32_dpp v93, v93, v93 row_shr:4 row_mask:0xf bank_mask:0xf
	v_fmac_f32_dpp v86, v86, v4 row_shr:8 row_mask:0xf bank_mask:0xf
	v_mul_f32_dpp v4, v4, v4 row_shr:8 row_mask:0xf bank_mask:0xf
	v_fmac_f32_dpp v87, v87, v5 row_shr:8 row_mask:0xf bank_mask:0xf
	v_mul_f32_dpp v5, v5, v5 row_shr:8 row_mask:0xf bank_mask:0xf
	v_fmac_f32_dpp v88, v88, v92 row_shr:8 row_mask:0xf bank_mask:0xf
	v_mul_f32_dpp v92, v92, v92 row_shr:8 row_mask:0xf bank_mask:0xf
	v_fmac_f32_dpp v89, v89, v93 row_shr:8 row_mask:0xf bank_mask:0xf
	v_mul_f32_dpp v93, v93, v93 row_shr:8 row_mask:0xf bank_mask:0xf

; #define LAS __attribute__((address_space(3)))
; __device__ __forceinline__ void lru_fused(const bf16* XC, const bf16* Wrg_t, const bf16* PROJ, bf16* YL, const float* b_a, const float* b_x, const float* sp8,
;                                           LAS unsigned char* lds, int tid, int lane, int wave, int vcu, int G) {
;     ...
;             const int l15 = (lane & 48) | 15;
; #pragma unroll
;             for (int c2 = 0; c2 < 2; ++c2)
; #pragma unroll
;                 for (int j = 0; j < 4; ++j) { const float a15 = __shfl(A[0][c2][j], l15), u15 = __shfl(U[0][c2][j], l15);
;                     U[1][c2][j] = A[1][c2][j] * u15 + U[1][c2][j]; A[1][c2][j] = A[1][c2][j] * a15; }
;             LAS float* xp = xch + (i & 1) * 512;
;             if (fr == 15) {
; #pragma unroll
;                 for (int c2 = 0; c2 < 2; ++c2) { *(LAS f32x4*)(xp + wave * 32 + 16 * c2 + 4 * fq) = (f32x4){A[1][c2][0], A[1][c2][1], A[1][c2][2], A[1][c2][3]};
;                     *(LAS f32x4*)(xp + 256 + wave * 32 + 16 * c2 + 4 * fq) = (f32x4){U[1][c2][0], U[1][c2][1], U[1][c2][2], U[1][c2][3]}; } }
	s_lshl_b32 s23, s24, 11
	s_waitcnt lgkmcnt(7)
	v_pk_mul_f32 v[100:101], v[100:101], v[90:91]
	s_waitcnt lgkmcnt(3)
	v_pk_fma_f32 v[86:87], v[4:5], v[104:105], v[86:87]
	v_pk_mul_f32 v[90:91], v[4:5], v[102:103]
	s_waitcnt lgkmcnt(1)
	v_pk_fma_f32 v[88:89], v[92:93], v[108:109], v[88:89]
	s_waitcnt lgkmcnt(0)
	v_pk_mul_f32 v[92:93], v[92:93], v[106:107]
	s_add_i32 s23, s23, 0
	s_and_saveexec_b64 s[66:67], s[2:3]
	s_cbranch_execz .LBB0_458
	s_lshl_b32 s25, s6, 2
	s_add_i32 s25, s23, s25
	v_lshl_add_u32 v3, v165, 2, s25
	ds_write_b128 v3, v[98:101] offset:36864
	ds_write_b128 v3, v[94:97] offset:37888
	ds_write_b128 v3, v[90:93] offset:36928
	ds_write_b128 v3, v[86:89] offset:37952
